# stick-breaking tile loop head: per-iteration lane address recomputation (4 LDS commit + 4 fetch addresses) hoisted to per-item lane offsets, fetches in scalar-base form
# speedup vs baseline: 1.0119x; 1.0060x over previous
; DI int otid() { int t = threadIdx.x; asm volatile("" : "+v"(t)); return t; }
; DI u32x4 tile_fetch(const bf16_t* __restrict__ src, size_t stride) {
;   const int c = otid(), row = c >> 3, col = (c & 7) * 8;
;   return *(const u32x4*)&src[(size_t)row * stride + col];
; }
; DI void tile_commit(bf16_t* dst, const u32x4& v) {
;   const int c = otid(), row = c >> 3, col = (c & 7) * 8;
;   *(u32x4*)&dst[row * LDT + col] = v;
; }
; DI void sb_item(const bf16_t* __restrict__ P, const bf16_t* __restrict__ VT, bf16_t* __restrict__ Y, int item, char* lds) {
;   const int tid = otid(), lane = tid & 63, wave = tid >> 6, l32 = lane & 31, hh = lane >> 5;
;   const int qb = item & 15, bh = item >> 4, b = bh >> 4, hd = bh & 15;
;   const int q0 = qb * 256 + wave * 32, qpos = q0 + l32;
;   const size_t tokbase = (size_t)b * SEQ;
;   bf16_t* Ks = (bf16_t*)lds;
;   bf16_t* VTs = Ks + 64 * LDT;
;   bf16x8 qf[4];
;   {
;     const bf16_t* qp = P + (tokbase + qpos) * LDP_O + hd * 64 + hh * 8;
; #pragma unroll
;     for (int s = 0; s < 4; ++s) qf[s] = *(const bf16x8*)(qp + s * 16);
;   }
;   f32x16 O[2], S[2];
; #pragma unroll
;   for (int dt = 0; dt < 2; ++dt)
; #pragma unroll
;     for (int e = 0; e < 16; ++e) O[dt][e] = 0.f;
;   float carry = 1.f;
;   const bf16_t* kb0 = P + tokbase * LDP_O + 1024 + hd * 64;
;   const bf16_t* vb0 = VT + (size_t)bh * 64 * SEQ;
;   const int kbs = 4 * qb + 3;
;   constexpr int TS = 64 * LDT;
;   u32x4 pfk = tile_fetch(kb0 + (size_t)kbs * 64 * LDP_O, LDP_O), pfv = tile_fetch(vb0 + kbs * 64, SEQ);
;   u32x4 pfk1 = tile_fetch(kb0 + (size_t)(kbs - 1) * 64 * LDP_O, LDP_O), pfv1 = tile_fetch(vb0 + (kbs - 1) * 64, SEQ);
;   __syncthreads();
;   tile_commit(Ks, pfk); tile_commit(Ks + TS, pfv); tile_commit(Ks + 2 * TS, pfk1); tile_commit(Ks + 3 * TS, pfv1);
;   if (kbs >= 3) {
;     pfk = tile_fetch(kb0 + (size_t)(kbs - 2) * 64 * LDP_O, LDP_O); pfv = tile_fetch(vb0 + (kbs - 2) * 64, SEQ);
;     pfk1 = tile_fetch(kb0 + (size_t)(kbs - 3) * 64 * LDP_O, LDP_O); pfv1 = tile_fetch(vb0 + (kbs - 3) * 64, SEQ);
;   }
;   __syncthreads();
;   int par = 0, fi = 0;
.LBB0_483:
	s_and_b32 s0, s7, 15
	s_lshl_b32 s1, s0, 2
	s_ashr_i32 s12, s8, 4
	s_add_i32 s9, s1, 5
	v_mov_b32_e32 v20, v167
	s_ashr_i32 s14, s8, 8
	s_lshl_b32 s1, s12, 6
	s_lshl_b32 s0, s0, 8
	s_ashr_i32 s15, s14, 31
	v_ashrrev_i32_e32 v0, 1, v20
	s_and_b32 s11, s1, 0x3c0
	s_or_b32 s10, s0, 0xff
	s_and_b32 s0, s8, 15
	v_and_b32_e32 v0, 0xffffffe0, v0
	s_lshl_b64 s[16:17], s[14:15], 12
	s_lshl_b32 s28, s11, 1
	s_lshl_b64 s[14:15], s[14:15], 24
	v_and_b32_e32 v21, 31, v20
	v_lshl_add_u32 v118, s0, 8, v0
	s_add_u32 s1, s60, s14
	v_or_b32_e32 v112, v118, v21
	s_addc_u32 s13, s61, s15
	v_ashrrev_i32_e32 v113, 31, v112
	s_add_u32 s44, s1, s28
	v_lshl_add_u64 v[114:115], s[16:17], 0, v[112:113]
	s_addc_u32 s45, s13, 0
	s_ashr_i32 s13, s12, 31
	v_lshlrev_b64 v[2:3], 12, v[114:115]
	s_lshl_b64 s[12:13], s[12:13], 19
	v_bfe_u32 v22, v20, 5, 1
	v_lshl_add_u64 v[2:3], s[60:61], 0, v[2:3]
	s_add_u32 s46, s82, s12
	v_lshl_add_u64 v[2:3], v[2:3], 0, s[28:29]
	v_lshlrev_b32_e32 v0, 4, v22
	s_addc_u32 s47, s83, s13
	s_lshl_b32 s1, s0, 2
	v_lshl_add_u64 v[2:3], v[2:3], 0, v[0:1]
	s_or_b32 s14, s1, 3
	v_mov_b32_e32 v0, v167
	global_load_dwordx4 v[80:83], v[2:3], off
	global_load_dwordx4 v[84:87], v[2:3], off offset:32
	global_load_dwordx4 v[88:91], v[2:3], off offset:64
	global_load_dwordx4 v[92:95], v[2:3], off offset:96
	s_lshl_b32 s12, s14, 18
	s_add_u32 s12, s44, s12
	v_ashrrev_i32_e32 v2, 3, v0
	v_ashrrev_i32_e32 v3, 31, v2
	s_addc_u32 s13, s45, 0
	v_lshlrev_b64 v[2:3], 12, v[2:3]
	v_lshlrev_b32_e32 v0, 4, v0
	v_lshl_add_u64 v[2:3], s[12:13], 0, v[2:3]
	v_and_b32_e32 v0, 0x70, v0
	v_lshl_add_u64 v[2:3], v[2:3], 0, v[0:1]
	v_mov_b32_e32 v0, v167
	global_load_dwordx4 v[2:5], v[2:3], off offset:2048
	s_lshl_b32 s12, s14, 7
	s_add_u32 s12, s46, s12
	v_ashrrev_i32_e32 v6, 3, v0
	v_ashrrev_i32_e32 v7, 31, v6
	s_addc_u32 s13, s47, 0
	v_lshlrev_b64 v[6:7], 13, v[6:7]
	v_lshlrev_b32_e32 v0, 4, v0
	v_lshl_add_u64 v[6:7], s[12:13], 0, v[6:7]
	v_and_b32_e32 v0, 0x70, v0
	v_lshl_add_u64 v[6:7], v[6:7], 0, v[0:1]
	s_or_b32 s14, s1, 2
	v_mov_b32_e32 v0, v167
	s_waitcnt lgkmcnt(0)
	global_load_dwordx4 v[6:9], v[6:7], off
	s_lshl_b32 s12, s14, 18
	s_add_u32 s12, s44, s12
	v_ashrrev_i32_e32 v10, 3, v0
	v_ashrrev_i32_e32 v11, 31, v10
	s_addc_u32 s13, s45, 0
	v_lshlrev_b64 v[10:11], 12, v[10:11]
	v_lshlrev_b32_e32 v0, 4, v0
	v_lshl_add_u64 v[10:11], s[12:13], 0, v[10:11]
	v_and_b32_e32 v0, 0x70, v0
	v_lshl_add_u64 v[10:11], v[10:11], 0, v[0:1]
	v_mov_b32_e32 v0, v167
	global_load_dwordx4 v[10:13], v[10:11], off offset:2048
	s_lshl_b32 s12, s14, 7
	s_add_u32 s12, s46, s12
	v_ashrrev_i32_e32 v14, 3, v0
	v_ashrrev_i32_e32 v15, 31, v14
	s_addc_u32 s13, s47, 0
	v_lshlrev_b64 v[14:15], 13, v[14:15]
	v_lshlrev_b32_e32 v0, 4, v0
	v_lshl_add_u64 v[14:15], s[12:13], 0, v[14:15]
	v_and_b32_e32 v0, 0x70, v0
	v_lshl_add_u64 v[14:15], v[14:15], 0, v[0:1]
	global_load_dwordx4 v[14:17], v[14:15], off
	v_mov_b32_e32 v0, v167
	s_waitcnt vmcnt(0)
	s_barrier
	s_or_b32 s1, s1, 1
	v_lshrrev_b32_e32 v18, 3, v0
	v_lshlrev_b32_e32 v0, 4, v0
	v_and_b32_e32 v0, 0x70, v0
	v_mad_u64_u32 v[18:19], s[12:13], v18, s92, v[0:1]
	v_mov_b32_e32 v0, v167
	v_mul_u32_u24_e32 v120, 0x48, v21
	v_lshl_add_u32 v121, v22, 3, v120
	v_lshlrev_b32_e32 v113, 2, v22
	v_cmp_eq_u32_e64 s[40:41], 0, v22
	v_cmp_eq_u32_e64 s[42:43], 0, v20
	v_or_b32_e32 v119, 31, v118
	v_mov_b32_e32 v117, 1.0
	s_mov_b64 s[34:35], 0
	ds_write_b128 v18, v[2:5]
	v_mov_b32_e32 v4, v1
	v_lshrrev_b32_e32 v2, 3, v0
	v_lshlrev_b32_e32 v0, 4, v0
	v_and_b32_e32 v0, 0x70, v0
	v_mad_u64_u32 v[2:3], s[12:13], v2, s92, v[0:1]
	v_mov_b32_e32 v0, v167
	v_mov_b32_e32 v5, v1
	ds_write_b128 v2, v[6:9] offset:9216
	v_mov_b32_e32 v6, v1
	v_lshrrev_b32_e32 v2, 3, v0
	v_lshlrev_b32_e32 v0, 4, v0
	v_and_b32_e32 v0, 0x70, v0
	v_mad_u64_u32 v[2:3], s[12:13], v2, s92, v[0:1]
	v_mov_b32_e32 v0, v167
	v_mov_b32_e32 v7, v1
	v_mov_b32_e32 v8, v1
	v_mov_b32_e32 v9, v1
	ds_write_b128 v2, v[10:13] offset:18432
	v_mov_b32_e32 v10, v1
	v_lshrrev_b32_e32 v2, 3, v0
	v_lshlrev_b32_e32 v0, 4, v0
	v_and_b32_e32 v0, 0x70, v0
	v_mad_u64_u32 v[2:3], s[12:13], v2, s92, v[0:1]
	v_mov_b32_e32 v0, v167
	s_lshl_b32 s12, s1, 18
	s_add_u32 s12, s44, s12
	s_addc_u32 s13, s45, 0
	ds_write_b128 v2, v[14:17] offset:27648
	s_lshl_b32 s1, s1, 7
	v_ashrrev_i32_e32 v2, 3, v0
	v_ashrrev_i32_e32 v3, 31, v2
	v_lshlrev_b64 v[2:3], 12, v[2:3]
	v_lshlrev_b32_e32 v0, 4, v0
	v_lshl_add_u64 v[2:3], s[12:13], 0, v[2:3]
	v_and_b32_e32 v0, 0x70, v0
	v_lshl_add_u64 v[2:3], v[2:3], 0, v[0:1]
	v_mov_b32_e32 v0, v167
	global_load_dwordx4 v[96:99], v[2:3], off offset:2048
	s_add_u32 s12, s46, s1
	v_ashrrev_i32_e32 v2, 3, v0
	v_ashrrev_i32_e32 v3, 31, v2
	s_addc_u32 s13, s47, 0
	v_lshlrev_b64 v[2:3], 13, v[2:3]
	v_lshlrev_b32_e32 v0, 4, v0
	v_lshl_add_u64 v[2:3], s[12:13], 0, v[2:3]
	v_and_b32_e32 v0, 0x70, v0
	v_lshl_add_u64 v[2:3], v[2:3], 0, v[0:1]
	v_mov_b32_e32 v0, v167
	global_load_dwordx4 v[100:103], v[2:3], off
	s_lshl_b32 s1, s0, 20
	s_add_u32 s12, s44, s1
	v_ashrrev_i32_e32 v2, 3, v0
	v_ashrrev_i32_e32 v3, 31, v2
	s_addc_u32 s13, s45, 0
	v_lshlrev_b64 v[2:3], 12, v[2:3]
	v_lshlrev_b32_e32 v0, 4, v0
	v_lshl_add_u64 v[2:3], s[12:13], 0, v[2:3]
	v_and_b32_e32 v0, 0x70, v0
	v_lshl_add_u64 v[2:3], v[2:3], 0, v[0:1]
	v_mov_b32_e32 v0, v167
	global_load_dwordx4 v[104:107], v[2:3], off offset:2048
	s_lshl_b32 s0, s0, 9
	s_add_u32 s0, s46, s0
	v_ashrrev_i32_e32 v2, 3, v0
	v_ashrrev_i32_e32 v3, 31, v2
	s_addc_u32 s1, s47, 0
	v_lshlrev_b64 v[2:3], 13, v[2:3]
	v_lshlrev_b32_e32 v0, 4, v0
	v_lshl_add_u64 v[2:3], s[0:1], 0, v[2:3]
	v_and_b32_e32 v0, 0x70, v0
	v_lshl_add_u64 v[2:3], v[2:3], 0, v[0:1]
	global_load_dwordx4 v[108:111], v[2:3], off
	v_mov_b32_e32 v14, v1
	v_mov_b32_e32 v15, v1
	v_mov_b32_e32 v0, v1
	v_mov_b32_e32 v2, v1
	v_mov_b32_e32 v3, v1
	v_mov_b32_e32 v11, v1
	v_mov_b32_e32 v12, v1
	v_mov_b32_e32 v13, v1
	v_mov_b64_e32 v[30:31], v[14:15]
	v_mov_b64_e32 v[46:47], v[14:15]
	s_mov_b32 s12, 0
	v_mov_b64_e32 v[28:29], v[12:13]
	v_mov_b64_e32 v[26:27], v[10:11]
	v_mov_b64_e32 v[24:25], v[8:9]
	v_mov_b64_e32 v[22:23], v[6:7]
	v_mov_b64_e32 v[20:21], v[4:5]
	v_mov_b64_e32 v[18:19], v[2:3]
	v_mov_b64_e32 v[16:17], v[0:1]
	v_mov_b64_e32 v[44:45], v[12:13]
	v_mov_b64_e32 v[42:43], v[10:11]
	v_mov_b64_e32 v[40:41], v[8:9]
	v_mov_b64_e32 v[38:39], v[6:7]
	v_mov_b64_e32 v[36:37], v[4:5]
	v_mov_b64_e32 v[34:35], v[2:3]
	v_mov_b64_e32 v[32:33], v[0:1]
	s_mov_b32 s13, 0
	v_lshrrev_b32_e32 v240, 3, v167
	v_lshlrev_b32_e32 v241, 4, v167
	v_and_b32_e32 v241, 0x70, v241
	v_mul_lo_u32 v242, v240, s92
	v_add_u32_e32 v242, v242, v241
	v_lshl_add_u32 v243, v240, 12, v241
	v_lshl_add_u32 v244, v240, 13, v241
	s_waitcnt lgkmcnt(0)
	s_barrier
	s_branch .LBB0_485

; DI int otid() { int t = threadIdx.x; asm volatile("" : "+v"(t)); return t; }
; DI u32x4 tile_fetch(const bf16_t* __restrict__ src, size_t stride) {
;   const int c = otid(), row = c >> 3, col = (c & 7) * 8;
;   return *(const u32x4*)&src[(size_t)row * stride + col];
; }
; DI void tile_commit(bf16_t* dst, const u32x4& v) {
;   const int c = otid(), row = c >> 3, col = (c & 7) * 8;
;   *(u32x4*)&dst[row * LDT + col] = v;
; }
; DI void sb_item(const bf16_t* __restrict__ P, const bf16_t* __restrict__ VT, bf16_t* __restrict__ Y, int item, char* lds) {
;     ...
;   for (int kb = kbs; kb >= 1; kb -= 2) {
;     const bf16_t* bcur = Ks + par * (4 * TS);
;     bf16_t* bnxt = Ks + (par ^ 1) * (4 * TS);
;     tile_commit(bnxt, pfk); tile_commit(bnxt + TS, pfv); tile_commit(bnxt + 2 * TS, pfk1); tile_commit(bnxt + 3 * TS, pfv1);
;     {
;       const int f0 = kb >= 5 ? kb - 4 : 1, f1 = kb >= 5 ? kb - 5 : 0;
;       pfk = tile_fetch(kb0 + (size_t)f0 * 64 * LDP_O, LDP_O); pfv = tile_fetch(vb0 + f0 * 64, SEQ);
;       pfk1 = tile_fetch(kb0 + (size_t)f1 * 64 * LDP_O, LDP_O); pfv1 = tile_fetch(vb0 + f1 * 64, SEQ);
;       __builtin_amdgcn_sched_barrier(0); }
.LBB0_485:
	s_mul_i32 s14, s12, 0x9000
	s_xor_b32 s12, s12, 1
	s_mul_i32 s0, s12, 0x9000
	v_add_u32_e32 v0, s0, v242
	s_add_i32 s9, s9, -2
	s_waitcnt vmcnt(3)
	ds_write_b128 v0, v[96:99]
	s_waitcnt vmcnt(2)
	ds_write_b128 v0, v[100:103] offset:9216
	s_waitcnt vmcnt(1)
	ds_write_b128 v0, v[104:107] offset:18432
	s_waitcnt vmcnt(0)
	ds_write_b128 v0, v[108:111] offset:27648
	s_max_u32 s0, s9, 5
	s_add_i32 s28, s0, -4
	s_lshl_b64 s[0:1], s[28:29], 18
	s_add_u32 s0, s44, s0
	s_addc_u32 s1, s45, s1
	global_load_dwordx4 v[96:99], v243, s[0:1] offset:2048
	s_lshl_b32 s28, s28, 6
	s_lshl_b64 s[0:1], s[28:29], 1
	s_add_u32 s0, s46, s0
	s_addc_u32 s1, s47, s1
	global_load_dwordx4 v[100:103], v244, s[0:1]
	s_sub_i32 s28, s9, 5
	s_max_i32 s28, s28, 0
	s_lshl_b64 s[0:1], s[28:29], 18
	s_add_u32 s0, s44, s0
	s_addc_u32 s1, s45, s1
	global_load_dwordx4 v[104:107], v243, s[0:1] offset:2048
	s_lshl_b32 s28, s28, 6
	s_lshl_b64 s[0:1], s[28:29], 1
	s_add_u32 s0, s46, s0
	s_addc_u32 s1, s47, s1
	global_load_dwordx4 v[108:111], v244, s[0:1]
	s_sub_i32 s0, s10, 63
	v_cmp_lt_i32_e32 vcc, s0, v119
	s_and_saveexec_b64 s[48:49], vcc
	s_cbranch_execz .LBB0_488
	v_cmp_lt_f32_e32 vcc, 0, v117
	s_cbranch_vccz .LBB0_488
	v_lshl_add_u32 v0, v121, 1, s14
	ds_read_b128 v[2:5], v0
	ds_read_b128 v[6:9], v0 offset:32
	ds_read_b128 v[10:13], v0 offset:64
	ds_read_b128 v[122:125], v0 offset:96
	ds_read_b128 v[64:67], v0 offset:4608
	ds_read_b128 v[126:129], v0 offset:4640
	ds_read_b128 v[130:133], v0 offset:4672
	ds_read_b128 v[134:137], v0 offset:4704
	s_setprio 1
	s_waitcnt lgkmcnt(7)
	v_mfma_f32_32x32x16_bf16 v[48:63], v[2:5], v[80:83], 0
	s_waitcnt lgkmcnt(3)
	v_mfma_f32_32x32x16_bf16 v[64:79], v[64:67], v[80:83], 0
	v_mfma_f32_32x32x16_bf16 v[48:63], v[6:9], v[84:87], v[48:63]
	s_waitcnt lgkmcnt(2)
	v_mfma_f32_32x32x16_bf16 v[64:79], v[126:129], v[84:87], v[64:79]
	v_mfma_f32_32x32x16_bf16 v[48:63], v[10:13], v[88:91], v[48:63]
	s_waitcnt lgkmcnt(1)
	v_mfma_f32_32x32x16_bf16 v[64:79], v[130:133], v[88:91], v[64:79]
	v_mfma_f32_32x32x16_bf16 v[48:63], v[122:125], v[92:95], v[48:63]
	s_waitcnt lgkmcnt(0)
	v_mfma_f32_32x32x16_bf16 v[64:79], v[134:137], v[92:95], v[64:79]
	s_setprio 0
	s_nop 10
	v_exp_f32_e32 v0, v64
	v_exp_f32_e32 v2, v65
	v_add_u32_e32 v13, s10, v113
	v_subrev_u32_e32 v3, 31, v13
	v_add_f32_e32 v0, 1.0, v0
	v_rcp_f32_e32 v0, v0
	v_cmp_lt_u32_e32 vcc, s10, v118
	s_cmp_eq_u64 vcc, exec
	s_cbranch_scc0 .Lsb_slow1
	v_add_f32_e32 v2, 1.0, v2
	v_mov_b32_e32 v3, v0
	v_sub_f32_e32 v0, 1.0, v0
	v_rcp_f32_e32 v64, v2
	v_exp_f32_e32 v4, v66
	v_sub_f32_e32 v65, 1.0, v64
	v_add_f32_e32 v2, 1.0, v4
	v_rcp_f32_e32 v66, v2
	v_exp_f32_e32 v4, v67
	v_sub_f32_e32 v67, 1.0, v66
	v_add_f32_e32 v2, 1.0, v4
	v_rcp_f32_e32 v2, v2
	v_exp_f32_e32 v4, v68
	v_mov_b32_e32 v68, v2
	v_sub_f32_e32 v122, 1.0, v2
	v_add_f32_e32 v2, 1.0, v4
	v_rcp_f32_e32 v5, v2
	v_exp_f32_e32 v4, v69
	v_sub_f32_e32 v12, 1.0, v5
	v_add_f32_e32 v2, 1.0, v4
	v_rcp_f32_e32 v14, v2
	v_exp_f32_e32 v4, v70
	v_sub_f32_e32 v15, 1.0, v14
	v_add_f32_e32 v2, 1.0, v4
	v_rcp_f32_e32 v69, v2
	v_exp_f32_e32 v4, v71
	v_sub_f32_e32 v70, 1.0, v69
	v_add_f32_e32 v2, 1.0, v4
	v_rcp_f32_e32 v71, v2
	v_exp_f32_e32 v4, v72
	v_sub_f32_e32 v72, 1.0, v71
	v_add_f32_e32 v2, 1.0, v4
	v_rcp_f32_e32 v6, v2
	v_exp_f32_e32 v4, v73
	v_sub_f32_e32 v73, 1.0, v6
	v_add_f32_e32 v2, 1.0, v4
	v_rcp_f32_e32 v8, v2
	v_exp_f32_e32 v4, v74
	v_sub_f32_e32 v74, 1.0, v8
	v_add_f32_e32 v2, 1.0, v4
	v_rcp_f32_e32 v2, v2
	v_exp_f32_e32 v4, v75
	v_mov_b32_e32 v75, v2
	v_sub_f32_e32 v123, 1.0, v2
	v_add_f32_e32 v2, 1.0, v4
	v_rcp_f32_e32 v2, v2
	v_exp_f32_e32 v4, v76
	v_mov_b32_e32 v76, v2
	v_sub_f32_e32 v124, 1.0, v2
	v_add_f32_e32 v2, 1.0, v4
	v_rcp_f32_e32 v7, v2
	v_exp_f32_e32 v4, v77
	v_sub_f32_e32 v77, 1.0, v7
	v_add_f32_e32 v2, 1.0, v4
	v_rcp_f32_e32 v2, v2
	v_exp_f32_e32 v4, v78
	v_mov_b32_e32 v78, v2
	v_sub_f32_e32 v125, 1.0, v2
	v_add_f32_e32 v2, 1.0, v4
	v_rcp_f32_e32 v2, v2
	v_exp_f32_e32 v4, v79
	v_mov_b32_e32 v79, v2
	v_sub_f32_e32 v126, 1.0, v2
	v_add_f32_e32 v2, 1.0, v4
	v_rcp_f32_e32 v127, v2
	v_mul_f32_e32 v7, v7, v78
	v_sub_f32_e32 v128, 1.0, v127
	v_mul_f32_e32 v2, v3, v64
	v_mul_f32_e32 v3, v66, v68
	v_mul_f32_e32 v4, v2, v3
	v_mov_b32_e32 v2, v4
	v_mov_b32_e32 v3, v4
	s_nop 1
	v_permlane32_swap_b32_e32 v2, v3
	v_cndmask_b32_e64 v2, v2, v3, s[40:41]
	v_mul_f32_e32 v3, v5, v14
	v_mul_f32_e32 v5, v69, v71
	v_mul_f32_e32 v3, v3, v5
	v_mov_b32_e32 v5, v3
	v_mov_b32_e32 v9, v3
	s_nop 1
	v_permlane32_swap_b32_e32 v5, v9
	v_cndmask_b32_e64 v5, v5, v9, s[40:41]
	v_mul_f32_e32 v9, v79, v127
	v_pk_mul_f32 v[6:7], v[6:7], v[8:9]
	v_mul_f32_e32 v10, v75, v76
	v_mov_b32_e32 v9, v7
	v_mov_b32_e32 v11, v7
	s_nop 1
	v_permlane32_swap_b32_e32 v9, v11
	v_cndmask_b32_e64 v11, v9, v11, s[40:41]
	v_pk_mul_f32 v[6:7], v[6:7], v[10:11]
	s_nop 0
	v_mov_b32_e32 v9, v6
	v_mov_b32_e32 v10, v6
	s_nop 1
	v_permlane32_swap_b32_e32 v9, v10
	v_cndmask_b32_e64 v116, v9, v10, s[40:41]
	v_mul_f32_e32 v9, v117, v11
	v_cndmask_b32_e64 v9, v117, v9, s[40:41]
	v_mul_f32_e32 v128, v128, v9
	v_mul_f32_e32 v9, v127, v9
	v_mul_f32_e32 v126, v126, v9
	v_mul_f32_e32 v9, v79, v9
	v_mul_f32_e32 v79, v125, v9
	v_mul_f32_e32 v9, v78, v9
	v_pk_mul_f32 v[6:7], v[6:7], v[116:117]
; DI float half_other(float x, int hh) { float a, b; half_swap(x, a, b); return hh ? a : b; }
; DI void sb_item(const bf16_t* __restrict__ P, const bf16_t* __restrict__ VT, bf16_t* __restrict__ Y, int item, char* lds) {
;     ...
;         float G[4], Go[4];
; #pragma unroll
;         for (int j = 0; j < 4; ++j) { G[j] = (st[4 * j] * st[4 * j + 1]) * (st[4 * j + 2] * st[4 * j + 3]); Go[j] = half_other(G[j], hh); }
;         float T = carry;
; #pragma unroll
;         for (int j = 3; j >= 0; --j) {
;           float run = hh ? T : T * Go[j];
; #pragma unroll
;           for (int e = 3; e >= 0; --e) {
;             const int idx = 4 * j + e;
;             S[kt2][idx] *= run;
;             run *= st[idx];
;           }
;           T *= G[j] * Go[j];
;         }
;         carry = T;
;       }
;       pv_tile(kcur + TS, S, O, l32, hh);
	v_mul_f32_e32 v77, v77, v9
	v_mul_f32_e32 v9, v7, v116
	v_pk_mul_f32 v[10:11], v[6:7], v[6:7] op_sel:[0,1] op_sel_hi:[1,0]
	v_cndmask_b32_e64 v9, v7, v9, s[40:41]
	v_mul_f32_e32 v6, v10, v5
	v_exp_f32_e32 v7, v48
	v_cndmask_b32_e64 v6, v10, v6, s[40:41]
	v_mul_f32_e32 v72, v72, v6
	v_mul_f32_e32 v6, v71, v6
	v_mul_f32_e32 v70, v70, v6
	v_mul_f32_e32 v6, v69, v6
	v_mul_f32_e32 v69, v15, v6
	v_mul_f32_e32 v6, v14, v6
	v_mul_f32_e32 v14, v3, v5
	v_add_f32_e32 v3, 1.0, v7
	v_rcp_f32_e32 v3, v3
	v_mul_f32_e32 v78, v124, v9
	v_mul_f32_e32 v9, v76, v9
	v_exp_f32_e32 v5, v49
	v_mul_f32_e32 v76, v123, v9
	v_mul_f32_e32 v9, v75, v9
	v_mul_f32_e32 v8, v8, v9
	v_mul_f32_e32 v73, v73, v8
	v_mov_b32_e32 v8, v3
	v_sub_f32_e32 v75, 1.0, v3
	v_add_f32_e32 v3, 1.0, v5
	v_rcp_f32_e32 v3, v3
	v_exp_f32_e32 v5, v50
	v_mul_f32_e32 v71, v12, v6
	v_mov_b32_e32 v6, v3
	v_sub_f32_e32 v116, 1.0, v3
	v_add_f32_e32 v3, 1.0, v5
	v_rcp_f32_e32 v12, v3
	v_exp_f32_e32 v5, v51
	v_sub_f32_e32 v117, 1.0, v12
	v_add_f32_e32 v3, 1.0, v5
	v_rcp_f32_e32 v48, v3
	v_exp_f32_e32 v5, v52
	v_sub_f32_e32 v123, 1.0, v48
	v_add_f32_e32 v3, 1.0, v5
	v_rcp_f32_e32 v7, v3
	v_exp_f32_e32 v5, v53
	v_sub_f32_e32 v124, 1.0, v7
	v_add_f32_e32 v3, 1.0, v5
	v_rcp_f32_e32 v3, v3
	v_exp_f32_e32 v5, v54
	v_mov_b32_e32 v54, v3
	v_sub_f32_e32 v125, 1.0, v3
	v_add_f32_e32 v3, 1.0, v5
	v_rcp_f32_e32 v3, v3
	v_exp_f32_e32 v5, v55
	v_mov_b32_e32 v55, v3
	v_sub_f32_e32 v127, 1.0, v3
	v_add_f32_e32 v3, 1.0, v5
	v_rcp_f32_e32 v3, v3
	v_exp_f32_e32 v5, v56
	v_mov_b32_e32 v56, v3
	v_sub_f32_e32 v129, 1.0, v3
	v_add_f32_e32 v3, 1.0, v5
	v_rcp_f32_e32 v49, v3
	v_exp_f32_e32 v5, v57
	v_sub_f32_e32 v52, 1.0, v49
	v_add_f32_e32 v3, 1.0, v5
	v_rcp_f32_e32 v53, v3
	v_exp_f32_e32 v5, v58
	v_sub_f32_e32 v57, 1.0, v53
	v_add_f32_e32 v3, 1.0, v5
	v_rcp_f32_e32 v58, v3
	v_exp_f32_e32 v5, v59
	v_sub_f32_e32 v59, 1.0, v58
	v_add_f32_e32 v3, 1.0, v5
	v_rcp_f32_e32 v3, v3
	v_exp_f32_e32 v5, v60
	v_mov_b32_e32 v60, v3
	v_sub_f32_e32 v130, 1.0, v3
	v_add_f32_e32 v3, 1.0, v5
	v_rcp_f32_e32 v5, v3
	v_mul_f32_e32 v74, v74, v9
	v_exp_f32_e32 v9, v61
	v_exp_f32_e32 v11, v62
	v_sub_f32_e32 v61, 1.0, v5
	v_add_f32_e32 v3, 1.0, v9
	v_rcp_f32_e32 v3, v3
	v_mul_f32_e32 v7, v7, v54
	v_sub_f32_e32 v62, 1.0, v3
	v_add_f32_e32 v9, 1.0, v11
	v_rcp_f32_e32 v15, v9
	v_exp_f32_e32 v11, v63
	v_sub_f32_e32 v63, 1.0, v15
	v_add_f32_e32 v9, 1.0, v11
	v_rcp_f32_e32 v11, v9
	s_nop 0
	v_sub_f32_e32 v13, 1.0, v11
	v_mul_f32_e32 v9, v55, v56
	v_mul_f32_e32 v9, v7, v9
	v_mov_b32_e32 v7, v9
	v_mov_b32_e32 v50, v9
	s_nop 1
	v_permlane32_swap_b32_e32 v7, v50
	v_cndmask_b32_e64 v7, v7, v50, s[40:41]
	v_mul_f32_e32 v49, v49, v53
	v_mul_f32_e32 v50, v58, v60
	v_mul_f32_e32 v131, v49, v50
	v_mov_b32_e32 v49, v131
	v_mov_b32_e32 v50, v131
	s_nop 1
	v_permlane32_swap_b32_e32 v49, v50
	v_cndmask_b32_e64 v132, v49, v50, s[40:41]
	v_pk_mul_f32 v[50:51], v[14:15], v[10:11]
	v_pk_mul_f32 v[4:5], v[4:5], v[2:3]
	v_mul_f32_e32 v10, v50, v2
	v_cndmask_b32_e64 v10, v50, v10, s[40:41]
	v_mul_f32_e32 v122, v122, v10
	v_mul_f32_e32 v10, v68, v10
	v_mul_f32_e32 v67, v67, v10
	v_mul_f32_e32 v10, v66, v10
	v_mul_f32_e32 v65, v65, v10
	v_mul_f32_e32 v10, v64, v10
	v_pk_mul_f32 v[4:5], v[4:5], v[50:51]
	v_mul_f32_e32 v0, v0, v10
	v_mov_b32_e32 v2, v5
	v_mov_b32_e32 v10, v5
	s_nop 1
	v_permlane32_swap_b32_e32 v2, v10
	v_cndmask_b32_e64 v2, v2, v10, s[40:41]
	v_mul_f32_e32 v10, v4, v2
	v_mul_f32_e32 v2, v5, v2
	v_mul_f32_e32 v49, v4, v2
	v_mul_f32_e32 v2, v49, v132
	v_cndmask_b32_e64 v10, v4, v10, s[40:41]
	v_cndmask_b32_e64 v2, v49, v2, s[40:41]
	v_mul_f32_e32 v64, v13, v10
	v_mul_f32_e32 v10, v11, v10
	v_mul_f32_e32 v66, v130, v2
	v_mul_f32_e32 v2, v60, v2
	v_mul_f32_e32 v63, v63, v10
	v_mul_f32_e32 v10, v15, v10
	v_mul_f32_e32 v59, v59, v2
	v_mul_f32_e32 v2, v58, v2
	v_mul_f32_e32 v3, v3, v10
	v_mul_f32_e32 v57, v57, v2
	v_mul_f32_e32 v2, v53, v2
	v_mul_f32_e32 v13, v131, v132
	v_mul_f32_e32 v61, v61, v3
	v_mul_f32_e32 v58, v52, v2
	v_pk_mul_f32 v[2:3], v[12:13], v[48:49]
	v_pk_mul_f32 v[4:5], v[8:9], v[6:7]
	v_mul_f32_e32 v62, v62, v10
	v_pk_mul_f32 v[52:53], v[4:5], v[2:3]
	s_nop 0
	v_mov_b32_e32 v2, v52
	v_mov_b32_e32 v4, v52
	s_nop 1
	v_permlane32_swap_b32_e32 v2, v4
	v_cndmask_b32_e64 v60, v2, v4, s[40:41]
	v_mul_f32_e32 v2, v3, v7
	v_cndmask_b32_e64 v2, v3, v2, s[40:41]
	v_mul_f32_e32 v7, v129, v2
	v_mul_f32_e32 v2, v56, v2
	v_mul_f32_e32 v56, v127, v2
	v_mul_f32_e32 v2, v55, v2
	v_mul_f32_e32 v55, v125, v2
	v_mul_f32_e32 v2, v54, v2
	v_mul_f32_e32 v54, v124, v2
	v_mul_f32_e32 v2, v53, v60
	v_cndmask_b32_e64 v2, v53, v2, s[40:41]
	v_mul_f32_e32 v68, v123, v2
	v_mul_f32_e32 v2, v48, v2
	v_mul_f32_e32 v123, v117, v2
	v_mul_f32_e32 v117, v12, v2
	v_lshlrev_b32_e32 v2, 1, v113
	v_lshlrev_b32_e32 v3, 1, v120
	v_add3_u32 v12, s14, v2, v3
	v_add_u32_e32 v124, 0x2000, v12
	v_add_u32_e32 v125, 0x3000, v12
	ds_read2_b64 v[2:5], v124 offset0:128 offset1:130
	ds_read2_b64 v[8:11], v124 offset0:132 offset1:134
	ds_read2_b64 v[12:15], v125 offset0:192 offset1:194
	ds_read2_b64 v[48:51], v125 offset0:196 offset1:198
	v_mul_f32_e32 v52, v52, v60
	v_mul_f32_e32 v116, v116, v117
	v_mul_f32_e32 v6, v6, v117
	v_mul_f32_e32 v117, v52, v53
	v_mul_f32_e32 v6, v75, v6
	s_branch .Lsb_join1
